# v067 + wave-uniform cinit/cbase test done on the scalar unit, probability-sum accumulators start from the first exp pairs
# baseline (speedup 1.0000x reference)
; template <bool WIN> ...
;     ...
;     const int tid = threadIdx.x, lane = tid & 63, l31 = lane & 31, hi = lane >> 5;
;     const int wid = __builtin_amdgcn_readfirstlane(tid >> 6), half = wid >> 2, wq = wid & 3;
;     const int qw = q0 + 32 * wq;
;     int qcol, kcol0, kcol1, vrow0, bhead;
;     if (WIN) { qcol = (2 * hsel + half) * 64; kcol0 = 512 + (hsel >> 1) * 64; kcol1 = kcol0; vrow0 = (hsel >> 1) * 64; bhead = 2 * hsel; }
;     else { qcol = 640 + (2 * hsel + half) * 64; kcol0 = 1152 + (2 * hsel) * 64; kcol1 = kcol0 + 64; vrow0 = 128 + hsel * 128; bhead = 8 + hsel; }
;     const ALAS float* lut = (const ALAS float*)(lds + OFF_LUT) + (WIN ? (bhead + half) : bhead) * LUTW;
;     const int t_lo = WIN ? (q0 >= 128 ? (q0 - 128) / 64 : 0) : 0;
;     const int t_hi = WIN ? ((q0 + 256) / 64 < S / 64 ? (q0 + 256) / 64 : S / 64) : S / 64;
;     const int NT = t_hi - t_lo;
;     const unsigned ldsb = (unsigned)(uintptr_t)lds;
;     const int drow = 8 * wid + (lane >> 3), dch = (lane & 7) ^ ((4 * wid + (lane >> 4)) & 7);
;     const bf16_t* kg = QK + ((size_t)((seq_base >> 6) + t_lo) * 26 * 64 + drow) * 64 + dch * 8 + kcol0 * 64;
;     const bf16_t* vg = VT + ((size_t)((seq_base >> 6) + t_lo) * 640 + vrow0 + drow) * 64 + dch * 8;
;     const unsigned dk = ldsb + wid * 1024;
;     ...
;     constexpr int NPW = WIN ? 2 : 4;
;     bf16x8 qfr[4];
;     { const int qrow = seq_base + qw + l31; const bf16_t* qp = QK + ((size_t)((qrow >> 6) * 26 + (qcol >> 6)) * 64 + (qrow & 63)) * 64 + hi * 8;
; #pragma unroll
;       for (int ds = 0; ds < 4; ++ds) qfr[ds] = *(const bf16x8*)(qp + ds * 16); }
;     ...
;     AT_DMA(0); if (NT > 1) AT_DMA(1); if (NT > 2) AT_DMA(2);
;     constexpr float THR = 8.0f;
;     float m_ref = WIN ? sinkp[2 * hsel + half] * LOG2E : 0.f;
;     float l_run = (WIN && hi == 0) ? 1.f : 0.f;
;     float cbase = 0.f;
;     f32x16 cvec;
; #pragma unroll
;     for (int r = 0; r < 16; ++r) cvec[r] = cbase - m_ref;
;     f32x16 o[NDB];
; #pragma unroll
;     for (int db = 0; db < NDB; ++db)
; #pragma unroll
;         for (int r = 0; r < 16; ++r) o[db][r] = 0.f;
;     const int krow = pi32(l31), fK = (krow >> 1) & 7, fV = (l31 >> 1) & 7;
;     int kx[4], vx[4];
; #pragma unroll
;     for (int c = 0; c < 4; ++c) { kx[c] = (WIN ? OFF_K0 : (half ? OFF_K1 : OFF_K0)) + krow * 128 + (((2 * c + hi) ^ fK) << 4); vx[c] = OFF_V + l31 * 128 + (((2 * c + hi) ^ fV) << 4); }
.LBB0_244:
	s_lshl_b32 s62, s33, 5
	s_lshl_b32 s20, s33, 2
	s_and_b32 s62, s62, 32
	v_readfirstlane_b32 s64, v230
	s_and_b32 s20, s20, 24
	s_add_i32 s62, s62, s22
	s_bfe_u32 s77, s64, 0x20006
	s_or_b32 s20, s20, s24
	s_lshl_b32 s62, s62, 7
	s_lshl_b32 s82, s77, 5
	s_lshl_b32 s20, s20, 11
	s_or_b32 s78, s82, s62
	s_and_b32 s20, s20, 0xe000
	s_lshr_b32 s76, s64, 8
	v_or_b32_e32 v4, s78, v185
	v_add_u32_e32 v170, s20, v4
	s_add_i32 s62, s76, s66
	v_ashrrev_i32_e32 v2, 6, v170
	v_mov_b32_e32 v0, s62
	v_mad_u64_u32 v[2:3], s[62:63], v2, 26, v[0:1]
	v_ashrrev_i32_e32 v3, 31, v2
	v_lshlrev_b64 v[2:3], 13, v[2:3]
	v_lshlrev_b32_e32 v0, 7, v4
	v_lshl_add_u64 v[2:3], s[6:7], 0, v[2:3]
	v_and_b32_e32 v4, 0x1f80, v0
	v_mov_b32_e32 v5, v1
	v_lshl_add_u64 v[2:3], v[2:3], 0, v[4:5]
	v_lshl_add_u64 v[2:3], v[2:3], 0, v[164:165]
	global_load_dwordx4 v[114:117], v[2:3], off offset:96
	global_load_dwordx4 v[118:121], v[2:3], off offset:64
	global_load_dwordx4 v[122:125], v[2:3], off offset:32
	global_load_dwordx4 v[126:129], v[2:3], off
	s_lshl_b32 s62, s31, 11
	s_and_b32 s62, s62, 0xffffc000
	s_or_b32 s62, s26, s62
	v_cndmask_b32_e64 v0, 0, 1, s[38:39]
	s_lshr_b32 s81, s62, 13
	v_readfirstlane_b32 s62, v0
	s_lshr_b32 s63, s64, 4
	s_lshl_b32 s83, s62, 12
	s_lshr_b32 s62, s64, 6
	s_and_b32 s63, s63, 4
	s_lshl_b32 s84, s62, 3
	v_bitop3_b32 v4, s63, v186, v189 bitop3:0x36
	s_lshr_b32 s63, s20, 6
	v_or_b32_e32 v0, s84, v188
	s_mul_i32 s20, s63, 0x680
	v_lshl_add_u64 v[2:3], s[20:21], 0, v[0:1]
	v_lshlrev_b64 v[2:3], 7, v[2:3]
	v_lshl_add_u64 v[2:3], s[6:7], 0, v[2:3]
	v_lshlrev_b32_e32 v4, 4, v4
	v_lshl_add_u64 v[2:3], v[2:3], 0, v[4:5]
	s_mul_i32 s20, s63, 0x280
	v_add_u32_e32 v6, s12, v0
	v_mov_b32_e32 v7, v1
	v_lshl_add_u64 v[2:3], v[2:3], 0, s[18:19]
	v_lshl_add_u64 v[6:7], v[6:7], 0, s[20:21]
	s_lshl_b32 s20, s62, 10
	s_mov_b64 s[62:63], 0x24000
	v_lshl_add_u64 v[8:9], v[2:3], 0, s[62:63]
	s_add_i32 s20, s20, 0
	s_mov_b32 s62, m0
	s_mov_b32 m0, s20
	s_nop 0
	global_load_lds_dwordx4 v[8:9], off
	s_mov_b32 m0, s62
	s_mov_b64 s[62:63], 0x26000
	v_lshlrev_b64 v[6:7], 7, v[6:7]
	v_lshl_add_u64 v[8:9], v[2:3], 0, s[62:63]
	s_add_i32 s62, s20, 0x2000
	v_lshl_add_u64 v[6:7], s[4:5], 0, v[6:7]
	s_mov_b32 s63, m0
	s_mov_b32 m0, s62
	s_nop 0
	global_load_lds_dwordx4 v[8:9], off
	s_mov_b32 m0, s63
	s_add_i32 s62, s20, 0x4000
	v_lshl_add_u64 v[6:7], v[6:7], 0, v[4:5]
	s_mov_b32 s63, m0
	s_mov_b32 m0, s62
	s_nop 0
	global_load_lds_dwordx4 v[6:7], off
	s_mov_b32 m0, s63
	s_add_i32 s62, s20, 0x6000
	v_lshl_add_u64 v[8:9], v[6:7], 0, s[40:41]
	s_mov_b32 s63, m0
	s_mov_b32 m0, s62
	s_nop 0
	global_load_lds_dwordx4 v[8:9], off
	s_mov_b32 m0, s63
	s_add_i32 s62, s20, 0x8000
	v_lshl_add_u64 v[8:9], v[2:3], 0, s[42:43]
	s_mov_b32 s63, m0
	s_mov_b32 m0, s62
	s_nop 0
	global_load_lds_dwordx4 v[8:9], off
	s_mov_b32 m0, s63
	s_add_i32 s62, s20, 0xa000
	v_lshl_add_u64 v[8:9], v[2:3], 0, s[46:47]
	s_mov_b32 s63, m0
	s_mov_b32 m0, s62
	s_nop 0
	global_load_lds_dwordx4 v[8:9], off
	s_mov_b32 m0, s63
	s_add_i32 s62, s20, 0xc000
	v_lshl_add_u64 v[8:9], v[6:7], 0, s[48:49]
	s_mov_b32 s63, m0
	s_mov_b32 m0, s62
	s_nop 0
	global_load_lds_dwordx4 v[8:9], off
	s_mov_b32 m0, s63
	s_add_i32 s62, s20, 0xe000
	v_lshl_add_u64 v[8:9], v[6:7], 0, s[50:51]
	s_mov_b32 s63, m0
	s_mov_b32 m0, s62
	s_nop 0
	global_load_lds_dwordx4 v[8:9], off
	s_mov_b32 m0, s63
	s_add_i32 s62, s20, 0x10000
	v_lshl_add_u64 v[8:9], v[2:3], 0, s[52:53]
	s_mov_b32 s63, m0
	s_mov_b32 m0, s62
	s_nop 0
	global_load_lds_dwordx4 v[8:9], off
	s_mov_b32 m0, s63
	s_add_i32 s62, s20, 0x12000
	v_lshl_add_u64 v[2:3], v[2:3], 0, s[54:55]
	s_mov_b32 s63, m0
	s_mov_b32 m0, s62
	s_nop 0
	global_load_lds_dwordx4 v[2:3], off
	s_mov_b32 m0, s63
	s_add_i32 s62, s20, 0x14000
	v_lshl_add_u64 v[2:3], v[6:7], 0, s[56:57]
	s_add_i32 s62, s20, 0x16000
	v_lshl_add_u64 v[2:3], v[6:7], 0, s[58:59]
	s_cmpk_lt_u32 s64, 0x100
	s_cselect_b64 s[62:63], -1, 0
	s_and_b64 s[64:65], s[62:63], exec
	s_cselect_b32 s64, 0, 0x2000
	s_add_i32 s67, s27, 0x20000
	v_mov_b32_e32 v2, s67
	ds_read_b32 v3, v2 offset:14336
	ds_read_b32 v2, v2 offset:16124
	v_or_b32_e32 v162, s64, v177
	v_mov_b32_e32 v14, v1
	v_mov_b32_e32 v15, v1
	s_waitcnt lgkmcnt(1)
	v_readfirstlane_b32 s79, v3
	s_waitcnt lgkmcnt(0)
	v_readfirstlane_b32 s80, v2
	v_add_u32_e32 v2, s84, v197
	v_mov_b32_e32 v3, v1
	v_lshlrev_b64 v[2:3], 7, v[2:3]
	v_mad_u64_u32 v[2:3], s[64:65], s81, v199, v[2:3]
	v_or_b32_e32 v2, v2, v4
	v_lshl_add_u64 v[172:173], s[36:37], 0, v[2:3]
	v_lshlrev_b64 v[2:3], 7, v[0:1]
	v_mad_u64_u32 v[2:3], s[64:65], s81, v200, v[2:3]
	s_or_b32 s64, s82, s83
	v_or_b32_e32 v2, v2, v4
	v_add_lshl_u32 v0, s64, v198, 2
	v_lshl_add_u64 v[174:175], s[16:17], 0, v[2:3]
	v_sub_u32_e32 v171, v195, v0
	s_sub_i32 s64, s28, s82
	v_mov_b32_e32 v0, v1
	v_mov_b32_e32 v2, v1
	v_mov_b32_e32 v3, v1
	v_mov_b32_e32 v4, v1
	v_mov_b32_e32 v6, v1
	v_mov_b32_e32 v7, v1
	v_mov_b32_e32 v8, v1
	v_mov_b32_e32 v9, v1
	v_mov_b32_e32 v10, v1
	v_mov_b32_e32 v11, v1
	v_mov_b32_e32 v12, v1
	v_mov_b32_e32 v13, v1
	v_mov_b64_e32 v[64:65], v[14:15]
	v_mov_b64_e32 v[48:49], v[14:15]
	v_mov_b64_e32 v[32:33], v[14:15]
	s_sub_i32 s81, s64, s83
	s_add_i32 s64, s29, s83
	v_mov_b64_e32 v[62:63], v[12:13]
	v_mov_b64_e32 v[60:61], v[10:11]
	v_mov_b64_e32 v[58:59], v[8:9]
	v_mov_b64_e32 v[56:57], v[6:7]
	v_mov_b64_e32 v[54:55], v[4:5]
	v_mov_b64_e32 v[52:53], v[2:3]
	v_mov_b64_e32 v[50:51], v[0:1]
	v_mov_b64_e32 v[46:47], v[12:13]
	v_mov_b64_e32 v[44:45], v[10:11]
	v_mov_b64_e32 v[42:43], v[8:9]
	v_mov_b64_e32 v[40:41], v[6:7]
	v_mov_b64_e32 v[38:39], v[4:5]
	v_mov_b64_e32 v[36:37], v[2:3]
	v_mov_b64_e32 v[34:35], v[0:1]
	v_mov_b64_e32 v[30:31], v[12:13]
	v_mov_b64_e32 v[28:29], v[10:11]
	v_mov_b64_e32 v[26:27], v[8:9]
	v_mov_b64_e32 v[24:25], v[6:7]
	v_mov_b64_e32 v[22:23], v[4:5]
	v_mov_b64_e32 v[20:21], v[2:3]
	v_mov_b64_e32 v[18:19], v[0:1]
	v_mov_b64_e32 v[16:17], v[14:15]
	s_add_i32 s82, s64, s82
	s_mov_b32 s83, 0
	s_mov_b32 s84, 0
	s_mov_b32 s85, 0x10000
	v_mov_b64_e32 v[14:15], v[12:13]
	v_mov_b64_e32 v[12:13], v[10:11]
	v_mov_b64_e32 v[10:11], v[8:9]
	v_mov_b64_e32 v[8:9], v[6:7]
	v_mov_b64_e32 v[6:7], v[4:5]
	v_mov_b64_e32 v[4:5], v[2:3]
	v_mov_b64_e32 v[2:3], v[0:1]
	v_mov_b32_e32 v0, 0
	v_mov_b32_e32 v196, 0
	v_mov_b32_e32 v202, 0
	s_mov_b32 s86, 0
	v_mov_b32_e32 v66, 0
	v_mov_b32_e32 v67, v1
	v_mov_b32_e32 v68, v1
	v_mov_b32_e32 v69, v1
	v_mov_b32_e32 v70, v1
	v_mov_b32_e32 v71, v1
	v_mov_b32_e32 v72, v1
	v_mov_b32_e32 v73, v1
	v_mov_b32_e32 v74, v1
	v_mov_b32_e32 v75, v1
	v_mov_b32_e32 v76, v1
	v_mov_b32_e32 v77, v1
	v_mov_b32_e32 v78, v1
	v_mov_b32_e32 v79, v1
	v_mov_b32_e32 v80, v1
	v_mov_b32_e32 v81, v1
	s_mov_b32 s100, 0
	s_mov_b32 s98, 0xfffec000
	s_mov_b32 s99, -1
	v_lshl_add_u64 v[172:173], v[172:173], 0, s[98:99]
	s_mov_b32 s98, 0xfffcc000
	s_waitcnt vmcnt(10)
	s_branch .LSPp_top

; template <bool WIN> ...
;     ...
;         const int k0 = (t_lo + tr) * 64;
;         const bool skip = WIN && (k0 > qw + 31 + 128 || k0 + 63 < qw - 128);
;         if (!skip) {
;             const bool near = WIN || ((k0 - (qw + 31)) < 128 && (qw - (k0 + 63)) < 128);
;             const float cinit = near ? 0.f : (k0 > qw ? cfar_hi : cfar_lo);
;             if (__builtin_expect(cinit != cbase, 0)) { cbase = cinit; asm volatile("" ::: "memory");
; #pragma unroll
;                 for (int r = 0; r < 16; ++r) cvec[r] = cbase - m_ref; }
.LSPp_skipv:
.LSPp_scal:
	s_add_i32 s64, s81, s83
	s_max_i32 s64, s64, s82
	s_cmpk_lt_i32 s64, 0x80
	s_cselect_b64 s[64:65], -1, 0
	s_cmp_gt_i32 s83, s78
	s_cselect_b32 s87, s80, s79
	s_cmp_lg_u64 s[64:65], 0
	s_cselect_b32 s98, 0, s87
	s_cmp_eq_u32 s98, s100
	s_cbranch_scc0 .LSPp_cin

; #define ALAS __attribute__((address_space(3)))
; template <bool WIN> ...
;     ...
;             float ls0 = 0.f, ls1 = 0.f;
;     ...
;             union PFU { u32x4 u; bf16x8 b; };
;             PFU p0, p1, p2, p3;
;             AT_EXP(s0, 0, p0);
; #pragma unroll
;             for (int kk = 0; kk < 2; ++kk)
; #pragma unroll
;                 for (int db = 0; db < NDB; ++db) vc[kk * NDB + db] = *(const ALAS bf16x8*)(sb + vx[kk + 2] + db * 4096);
;             __builtin_amdgcn_sched_barrier(0);
; #pragma unroll
;             for (int db = 0; db < NDB; ++db) o[db] = __builtin_amdgcn_mfma_f32_32x32x16_bf16(va[db], p0.b, o[db], 0, 0, 0);
;             AT_EXP(s0, 8, p1);
;             __builtin_amdgcn_sched_barrier(0);
; #pragma unroll
;             for (int db = 0; db < NDB; ++db) o[db] = __builtin_amdgcn_mfma_f32_32x32x16_bf16(va[NDB + db], p1.b, o[db], 0, 0, 0);
;             AT_EXP(s1, 0, p2);
;             __builtin_amdgcn_sched_barrier(0);
; #pragma unroll
;             for (int db = 0; db < NDB; ++db) o[db] = __builtin_amdgcn_mfma_f32_32x32x16_bf16(vc[db], p2.b, o[db], 0, 0, 0);
;             AT_EXP(s1, 8, p3);
;             __builtin_amdgcn_sched_barrier(0);
; #pragma unroll
;             for (int db = 0; db < NDB; ++db) o[db] = __builtin_amdgcn_mfma_f32_32x32x16_bf16(vc[NDB + db], p3.b, o[db], 0, 0, 0);
;             __builtin_amdgcn_sched_barrier(0);
;     ...
;             l_run += ls0 + ls1;
.LSPp_pv:
	s_cmp_eq_u32 s86, 0
	s_cbranch_scc1 .LSPp_pure
	s_waitcnt lgkmcnt(4)
	v_mfma_f32_32x32x16_bf16 v[50:65], v[146:149], v[238:241], v[50:65]
	v_exp_f32_e32 v98, v98
	v_exp_f32_e32 v99, v99
	v_mfma_f32_32x32x16_bf16 v[34:49], v[150:153], v[238:241], v[34:49]
	v_exp_f32_e32 v100, v100
	v_exp_f32_e32 v101, v101
	v_mfma_f32_32x32x16_bf16 v[18:33], v[154:157], v[238:241], v[18:33]
	v_exp_f32_e32 v102, v102
	v_exp_f32_e32 v103, v103
	v_add_f32_e32 v228, v98, v100
	v_add_f32_e32 v229, v99, v101
	v_mfma_f32_32x32x16_bf16 v[2:17], v[158:161], v[238:241], v[2:17]
	v_exp_f32_e32 v104, v104
	v_exp_f32_e32 v105, v105
	v_add_f32_e32 v228, v228, v102
	v_add_f32_e32 v229, v229, v103
	v_add3_u32 v236, s99, v183, v187
	ds_read_b128 v[146:149], v236 offset:16384
	ds_read_b128 v[150:153], v236 offset:20480
	ds_read_b128 v[154:157], v236 offset:24576
	ds_read_b128 v[158:161], v236 offset:28672
	s_waitcnt lgkmcnt(4)
	v_mfma_f32_32x32x16_bf16 v[50:65], v[130:133], v[242:245], v[50:65]
	v_exp_f32_e32 v106, v106
	v_exp_f32_e32 v107, v107
	v_add_f32_e32 v228, v228, v104
	v_add_f32_e32 v229, v229, v105
	v_cvt_pk_bf16_f32 v238, v98, v99
	v_mfma_f32_32x32x16_bf16 v[34:49], v[134:137], v[242:245], v[34:49]
	v_exp_f32_e32 v108, v108
	v_exp_f32_e32 v109, v109
	v_add_f32_e32 v228, v228, v106
	v_add_f32_e32 v229, v229, v107
	v_cvt_pk_bf16_f32 v239, v100, v101
	v_mfma_f32_32x32x16_bf16 v[18:33], v[138:141], v[242:245], v[18:33]
	v_exp_f32_e32 v110, v110
	v_exp_f32_e32 v111, v111
	v_add_f32_e32 v228, v228, v108
	v_add_f32_e32 v229, v229, v109
	v_cvt_pk_bf16_f32 v240, v102, v103
	v_mfma_f32_32x32x16_bf16 v[2:17], v[142:145], v[242:245], v[2:17]
	v_exp_f32_e32 v112, v112
	v_exp_f32_e32 v113, v113
	v_add_f32_e32 v228, v228, v110
	v_add_f32_e32 v229, v229, v111
	v_cvt_pk_bf16_f32 v241, v104, v105
	v_add3_u32 v237, s99, v190, v187
	ds_read_b128 v[130:133], v237 offset:16384
	ds_read_b128 v[134:137], v237 offset:20480
	ds_read_b128 v[138:141], v237 offset:24576
	ds_read_b128 v[142:145], v237 offset:28672
	s_waitcnt lgkmcnt(4)
	v_mfma_f32_32x32x16_bf16 v[50:65], v[146:149], v[246:249], v[50:65]
	v_exp_f32_e32 v82, v82
	v_exp_f32_e32 v83, v83
	v_add_f32_e32 v228, v228, v112
	v_add_f32_e32 v229, v229, v113
	v_cvt_pk_bf16_f32 v242, v106, v107
	v_mfma_f32_32x32x16_bf16 v[34:49], v[150:153], v[246:249], v[34:49]
	v_exp_f32_e32 v84, v84
	v_exp_f32_e32 v85, v85
	v_add_f32_e32 v228, v228, v82
	v_add_f32_e32 v229, v229, v83
	v_cvt_pk_bf16_f32 v243, v108, v109
	v_mfma_f32_32x32x16_bf16 v[18:33], v[154:157], v[246:249], v[18:33]
	v_exp_f32_e32 v86, v86
	v_exp_f32_e32 v87, v87
	v_add_f32_e32 v228, v228, v84
	v_add_f32_e32 v229, v229, v85
	v_cvt_pk_bf16_f32 v244, v110, v111
	v_mfma_f32_32x32x16_bf16 v[2:17], v[158:161], v[246:249], v[2:17]
	v_exp_f32_e32 v88, v88
	v_exp_f32_e32 v89, v89
	v_add_f32_e32 v228, v228, v86
	v_add_f32_e32 v229, v229, v87
	v_cvt_pk_bf16_f32 v245, v112, v113
	s_waitcnt lgkmcnt(0)
	v_mfma_f32_32x32x16_bf16 v[50:65], v[130:133], v[250:253], v[50:65]
	v_exp_f32_e32 v90, v90
	v_exp_f32_e32 v91, v91
	v_add_f32_e32 v228, v228, v88
	v_add_f32_e32 v229, v229, v89
	v_cvt_pk_bf16_f32 v246, v82, v83
	v_mfma_f32_32x32x16_bf16 v[34:49], v[134:137], v[250:253], v[34:49]
	v_exp_f32_e32 v92, v92
	v_exp_f32_e32 v93, v93
	v_add_f32_e32 v228, v228, v90
	v_add_f32_e32 v229, v229, v91
	v_cvt_pk_bf16_f32 v247, v84, v85
	v_mfma_f32_32x32x16_bf16 v[18:33], v[138:141], v[250:253], v[18:33]
	v_exp_f32_e32 v94, v94
	v_exp_f32_e32 v95, v95
	v_add_f32_e32 v228, v228, v92
	v_add_f32_e32 v229, v229, v93
	v_cvt_pk_bf16_f32 v248, v86, v87
	v_mfma_f32_32x32x16_bf16 v[2:17], v[142:145], v[250:253], v[2:17]
	v_exp_f32_e32 v96, v96
	v_exp_f32_e32 v97, v97
	v_add_f32_e32 v228, v228, v94
	v_add_f32_e32 v229, v229, v95
	v_cvt_pk_bf16_f32 v249, v88, v89
	v_add_f32_e32 v228, v228, v96
	v_add_f32_e32 v229, v229, v97
	v_cvt_pk_bf16_f32 v250, v90, v91
	v_cvt_pk_bf16_f32 v251, v92, v93
	v_cvt_pk_bf16_f32 v252, v94, v95
	v_cvt_pk_bf16_f32 v253, v96, v97
	v_add_f32_e32 v228, v228, v229
	v_cmp_nge_f32_e32 vcc, 0x53800000, v228
	s_cbranch_vccnz .LSPp_redo
	s_add_i32 s86, s86, 1
	s_add_i32 s85, s85, 0x8000
	s_addk_i32 s84, 0x100
	s_add_i32 s83, s83, 64
	s_sub_i32 s82, s82, 64
	v_add_f32_e32 v0, v0, v228
	v_lshl_add_u64 v[172:173], v[172:173], 0, s[48:49]
	s_cmpk_eq_u32 s84, 0x8000
	v_lshl_add_u64 v[174:175], v[174:175], 0, s[60:61]
	s_cbranch_scc0 .LSPp_top
	s_branch .LSPp_exit

; template <bool WIN> ...
;     ...
;             const float cinit = near ? 0.f : (k0 > qw ? cfar_hi : cfar_lo);
;             if (__builtin_expect(cinit != cbase, 0)) { cbase = cinit; asm volatile("" ::: "memory");
; #pragma unroll
;                 for (int r = 0; r < 16; ++r) cvec[r] = cbase - m_ref; }
.LSPp_cin:
	v_mov_b32_e32 v98, s98
	s_mov_b32 s100, s98
	v_sub_f32_e32 v82, v98, v196
	v_mov_b32_e32 v202, v98
	v_mov_b32_e32 v66, v82
	v_mov_b32_e32 v67, v82
	v_mov_b32_e32 v68, v82
	v_mov_b32_e32 v69, v82
	v_mov_b32_e32 v70, v82
	v_mov_b32_e32 v71, v82
	v_mov_b32_e32 v72, v82
	v_mov_b32_e32 v73, v82
	v_mov_b32_e32 v74, v82
	v_mov_b32_e32 v75, v82
	v_mov_b32_e32 v76, v82
	v_mov_b32_e32 v77, v82
	v_mov_b32_e32 v78, v82
	v_mov_b32_e32 v79, v82
	v_mov_b32_e32 v80, v82
	v_mov_b32_e32 v81, v82
	s_branch .LSPp_qk

; template <bool WIN> ...
;     ...
;     const int tid = threadIdx.x, lane = tid & 63, l31 = lane & 31, hi = lane >> 5;
;     const int wid = __builtin_amdgcn_readfirstlane(tid >> 6), half = wid >> 2, wq = wid & 3;
;     const int qw = q0 + 32 * wq;
;     int qcol, kcol0, kcol1, vrow0, bhead;
;     if (WIN) { qcol = (2 * hsel + half) * 64; kcol0 = 512 + (hsel >> 1) * 64; kcol1 = kcol0; vrow0 = (hsel >> 1) * 64; bhead = 2 * hsel; }
;     else { qcol = 640 + (2 * hsel + half) * 64; kcol0 = 1152 + (2 * hsel) * 64; kcol1 = kcol0 + 64; vrow0 = 128 + hsel * 128; bhead = 8 + hsel; }
;     const ALAS float* lut = (const ALAS float*)(lds + OFF_LUT) + (WIN ? (bhead + half) : bhead) * LUTW;
;     const int t_lo = WIN ? (q0 >= 128 ? (q0 - 128) / 64 : 0) : 0;
;     const int t_hi = WIN ? ((q0 + 256) / 64 < S / 64 ? (q0 + 256) / 64 : S / 64) : S / 64;
;     const int NT = t_hi - t_lo;
;     const unsigned ldsb = (unsigned)(uintptr_t)lds;
;     const int drow = 8 * wid + (lane >> 3), dch = (lane & 7) ^ ((4 * wid + (lane >> 4)) & 7);
;     const bf16_t* kg = QK + ((size_t)((seq_base >> 6) + t_lo) * 26 * 64 + drow) * 64 + dch * 8 + kcol0 * 64;
;     const bf16_t* vg = VT + ((size_t)((seq_base >> 6) + t_lo) * 640 + vrow0 + drow) * 64 + dch * 8;
;     const unsigned dk = ldsb + wid * 1024;
;     ...
;     constexpr int NPW = WIN ? 2 : 4;
;     bf16x8 qfr[4];
;     { const int qrow = seq_base + qw + l31; const bf16_t* qp = QK + ((size_t)((qrow >> 6) * 26 + (qcol >> 6)) * 64 + (qrow & 63)) * 64 + hi * 8;
; #pragma unroll
;       for (int ds = 0; ds < 4; ++ds) qfr[ds] = *(const bf16x8*)(qp + ds * 16); }
;     ...
;     AT_DMA(0); if (NT > 1) AT_DMA(1); if (NT > 2) AT_DMA(2);
;     constexpr float THR = 8.0f;
;     float m_ref = WIN ? sinkp[2 * hsel + half] * LOG2E : 0.f;
;     float l_run = (WIN && hi == 0) ? 1.f : 0.f;
;     float cbase = 0.f;
;     f32x16 cvec;
; #pragma unroll
;     for (int r = 0; r < 16; ++r) cvec[r] = cbase - m_ref;
;     f32x16 o[NDB];
; #pragma unroll
;     for (int db = 0; db < NDB; ++db)
; #pragma unroll
;         for (int r = 0; r < 16; ++r) o[db][r] = 0.f;
;     const int krow = pi32(l31), fK = (krow >> 1) & 7, fV = (l31 >> 1) & 7;
;     int kx[4], vx[4];
; #pragma unroll
;     for (int c = 0; c < 4; ++c) { kx[c] = (WIN ? OFF_K0 : (half ? OFF_K1 : OFF_K0)) + krow * 128 + (((2 * c + hi) ^ fK) << 4); vx[c] = OFF_V + l31 * 128 + (((2 * c + hi) ^ fV) << 4); }
.LBB0_268:
	v_readfirstlane_b32 s33, v230
	s_lshl_b32 s26, s25, 13
	s_bfe_u32 s27, s33, 0x20006
	s_add_i32 s26, s26, s23
	s_lshl_b32 s28, s27, 5
	s_and_b32 s26, s26, 0xfffff800
	s_or_b32 s28, s28, s22
	s_add_i32 s29, s26, 0x10000
	s_lshr_b32 s26, s33, 8
	v_or_b32_e32 v10, s28, v185
	v_or_b32_e32 v170, s29, v10
	s_add_i32 s30, s26, s66
	v_ashrrev_i32_e32 v2, 6, v170
	v_mov_b32_e32 v0, s30
	v_mad_u64_u32 v[2:3], s[30:31], v2, 26, v[0:1]
	v_ashrrev_i32_e32 v3, 31, v2
	v_lshlrev_b64 v[2:3], 13, v[2:3]
	v_lshlrev_b32_e32 v0, 7, v10
	v_lshl_add_u64 v[2:3], s[6:7], 0, v[2:3]
	v_and_b32_e32 v4, 0x1f80, v0
	v_mov_b32_e32 v5, v1
	v_lshl_add_u64 v[2:3], v[2:3], 0, v[4:5]
	v_lshl_add_u64 v[2:3], v[2:3], 0, v[164:165]
	global_load_dwordx4 v[114:117], v[2:3], off offset:96
	global_load_dwordx4 v[118:121], v[2:3], off offset:64
	global_load_dwordx4 v[122:125], v[2:3], off offset:32
	global_load_dwordx4 v[126:129], v[2:3], off
	s_lshr_b32 s62, s33, 6
	s_lshr_b32 s30, s33, 4
	v_lshl_or_b32 v0, s62, 3, v188
	s_and_b32 s30, s30, 4
	s_ashr_i32 s76, s29, 6
	v_bitop3_b32 v4, s30, v186, v189 bitop3:0x36
	v_mad_i64_i32 v[2:3], s[30:31], s76, v194, v[0:1]
	v_lshlrev_b64 v[2:3], 7, v[2:3]
	v_lshl_add_u64 v[2:3], s[6:7], 0, v[2:3]
	v_lshlrev_b32_e32 v4, 4, v4
	s_mul_hi_i32 s31, s76, 0x280
	s_mul_i32 s30, s76, 0x280
	v_lshl_add_u64 v[2:3], v[2:3], 0, v[4:5]
	s_or_b64 s[30:31], s[30:31], s[12:13]
	v_lshl_add_u64 v[2:3], v[2:3], 0, s[18:19]
	v_lshl_add_u64 v[6:7], s[30:31], 0, v[0:1]
	s_lshl_b32 s29, s62, 10
	v_lshlrev_b64 v[6:7], 7, v[6:7]
	v_lshl_add_u64 v[8:9], v[2:3], 0, s[36:37]
	s_add_i32 s29, s29, 0
	s_mov_b32 s30, m0
	s_mov_b32 m0, s29
	s_nop 0
	global_load_lds_dwordx4 v[8:9], off
	s_mov_b32 m0, s30
	v_lshl_add_u64 v[6:7], s[4:5], 0, v[6:7]
	v_lshl_add_u64 v[8:9], v[2:3], 0, s[38:39]
	s_add_i32 s30, s29, 0x2000
	s_mov_b32 s31, m0
	s_mov_b32 m0, s30
	s_nop 0
	global_load_lds_dwordx4 v[8:9], off
	s_mov_b32 m0, s31
	v_lshl_add_u64 v[6:7], v[6:7], 0, v[4:5]
	s_add_i32 s30, s29, 0x4000
	s_mov_b32 s31, m0
	s_mov_b32 m0, s30
	s_nop 0
	global_load_lds_dwordx4 v[6:7], off
	s_mov_b32 m0, s31
	v_lshl_add_u64 v[8:9], v[6:7], 0, s[40:41]
	s_add_i32 s30, s29, 0x6000
	s_mov_b32 s31, m0
	s_mov_b32 m0, s30
	s_nop 0
	global_load_lds_dwordx4 v[8:9], off
	s_mov_b32 m0, s31
	s_add_i32 s30, s29, 0x8000
	v_lshl_add_u64 v[8:9], v[2:3], 0, s[42:43]
	s_mov_b32 s31, m0
	s_mov_b32 m0, s30
	s_nop 0
	global_load_lds_dwordx4 v[8:9], off
	s_mov_b32 m0, s31
	v_lshl_add_u64 v[8:9], v[2:3], 0, s[46:47]
	s_add_i32 s30, s29, 0xa000
	s_mov_b32 s31, m0
	s_mov_b32 m0, s30
	s_nop 0
	global_load_lds_dwordx4 v[8:9], off
	s_mov_b32 m0, s31
	v_lshl_add_u64 v[8:9], v[6:7], 0, s[48:49]
	s_add_i32 s30, s29, 0xc000
	s_mov_b32 s31, m0
	s_mov_b32 m0, s30
	s_nop 0
	global_load_lds_dwordx4 v[8:9], off
	s_mov_b32 m0, s31
	v_lshl_add_u64 v[8:9], v[6:7], 0, s[50:51]
	s_add_i32 s30, s29, 0xe000
	s_mov_b32 s31, m0
	s_mov_b32 m0, s30
	s_nop 0
	global_load_lds_dwordx4 v[8:9], off
	s_mov_b32 m0, s31
	s_add_i32 s30, s29, 0x10000
	v_lshl_add_u64 v[8:9], v[2:3], 0, s[52:53]
	s_mov_b32 s31, m0
	s_mov_b32 m0, s30
	s_nop 0
	global_load_lds_dwordx4 v[8:9], off
	s_mov_b32 m0, s31
	v_lshl_add_u64 v[2:3], v[2:3], 0, s[54:55]
	s_add_i32 s30, s29, 0x12000
	s_mov_b32 s31, m0
	s_mov_b32 m0, s30
	s_nop 0
	global_load_lds_dwordx4 v[2:3], off
	s_mov_b32 m0, s31
	v_lshl_add_u64 v[2:3], v[6:7], 0, s[56:57]
	s_add_i32 s30, s29, 0x14000
	v_lshl_add_u64 v[2:3], v[6:7], 0, s[58:59]
	s_add_i32 s30, s29, 0x16000
	ds_read_b32 v2, v197 offset:14336
	ds_read_b32 v3, v197 offset:16124
	s_cmpk_lt_u32 s33, 0x100
	s_cselect_b64 s[62:63], -1, 0
	s_and_b64 s[30:31], s[62:63], exec
	s_cselect_b32 s30, 0, 0x2000
	v_or_b32_e32 v162, s30, v177
	s_waitcnt lgkmcnt(1)
	v_readfirstlane_b32 s30, v2
	s_waitcnt lgkmcnt(0)
	v_readfirstlane_b32 s31, v3
	v_lshlrev_b64 v[2:3], 7, v[0:1]
	v_mad_i64_i32 v[6:7], s[64:65], s76, v198, v[2:3]
	v_mad_i64_i32 v[2:3], s[64:65], s76, v199, v[2:3]
	v_or_b32_e32 v6, v6, v4
	v_or_b32_e32 v2, v2, v4
	v_lshlrev_b32_e32 v0, 2, v10
	v_mov_b32_e32 v14, v1
	v_mov_b32_e32 v15, v1
	v_lshl_add_u64 v[172:173], s[20:21], 0, v[6:7]
	v_lshl_add_u64 v[174:175], s[16:17], 0, v[2:3]
	v_sub_u32_e32 v171, v195, v0
	v_mov_b32_e32 v0, v1
	v_mov_b32_e32 v2, v1
	v_mov_b32_e32 v3, v1
	v_mov_b32_e32 v4, v1
	v_mov_b32_e32 v6, v1
	v_mov_b32_e32 v7, v1
	v_mov_b32_e32 v8, v1
	v_mov_b32_e32 v9, v1
	v_mov_b32_e32 v10, v1
	v_mov_b32_e32 v11, v1
	v_mov_b32_e32 v12, v1
	v_mov_b32_e32 v13, v1
	v_mov_b64_e32 v[64:65], v[14:15]
	v_mov_b64_e32 v[48:49], v[14:15]
	v_mov_b64_e32 v[32:33], v[14:15]
	v_mov_b64_e32 v[62:63], v[12:13]
	v_mov_b64_e32 v[60:61], v[10:11]
	v_mov_b64_e32 v[58:59], v[8:9]
	v_mov_b64_e32 v[56:57], v[6:7]
	v_mov_b64_e32 v[54:55], v[4:5]
	v_mov_b64_e32 v[52:53], v[2:3]
	v_mov_b64_e32 v[50:51], v[0:1]
	v_mov_b64_e32 v[46:47], v[12:13]
	v_mov_b64_e32 v[44:45], v[10:11]
	v_mov_b64_e32 v[42:43], v[8:9]
	v_mov_b64_e32 v[40:41], v[6:7]
	v_mov_b64_e32 v[38:39], v[4:5]
	v_mov_b64_e32 v[36:37], v[2:3]
	v_mov_b64_e32 v[34:35], v[0:1]
	v_mov_b64_e32 v[30:31], v[12:13]
	v_mov_b64_e32 v[28:29], v[10:11]
	v_mov_b64_e32 v[26:27], v[8:9]
	v_mov_b64_e32 v[24:25], v[6:7]
	v_mov_b64_e32 v[22:23], v[4:5]
	v_mov_b64_e32 v[20:21], v[2:3]
	v_mov_b64_e32 v[18:19], v[0:1]
	v_mov_b64_e32 v[16:17], v[14:15]
	s_add_i32 s33, s28, 0x9f
	s_add_i32 s67, s28, 0xffffff41
	s_mov_b32 s76, 0
	s_mov_b32 s77, 0
	s_mov_b32 s78, 0x10000
	v_mov_b64_e32 v[14:15], v[12:13]
	v_mov_b64_e32 v[12:13], v[10:11]
	v_mov_b64_e32 v[10:11], v[8:9]
	v_mov_b64_e32 v[8:9], v[6:7]
	v_mov_b64_e32 v[6:7], v[4:5]
	v_mov_b64_e32 v[4:5], v[2:3]
	v_mov_b64_e32 v[2:3], v[0:1]
	v_mov_b32_e32 v0, 0
	v_mov_b32_e32 v201, 0
	v_mov_b32_e32 v202, 0
	s_mov_b32 s79, 0
	v_mov_b32_e32 v66, 0
	v_mov_b32_e32 v67, v1
	v_mov_b32_e32 v68, v1
	v_mov_b32_e32 v69, v1
	v_mov_b32_e32 v70, v1
	v_mov_b32_e32 v71, v1
	v_mov_b32_e32 v72, v1
	v_mov_b32_e32 v73, v1
	v_mov_b32_e32 v74, v1
	v_mov_b32_e32 v75, v1
	v_mov_b32_e32 v76, v1
	v_mov_b32_e32 v77, v1
	v_mov_b32_e32 v78, v1
	v_mov_b32_e32 v79, v1
	v_mov_b32_e32 v80, v1
	v_mov_b32_e32 v81, v1
	s_mov_b32 s100, 0
	s_mov_b32 s98, 0xfffec000
	s_mov_b32 s99, -1
	v_lshl_add_u64 v[172:173], v[172:173], 0, s[98:99]
	s_mov_b32 s98, 0xfffcc000
	s_waitcnt vmcnt(10)
	s_branch .LSPs_top

; template <bool WIN> ...
;     ...
;         const int k0 = (t_lo + tr) * 64;
;         const bool skip = WIN && (k0 > qw + 31 + 128 || k0 + 63 < qw - 128);
;         if (!skip) {
;             const bool near = WIN || ((k0 - (qw + 31)) < 128 && (qw - (k0 + 63)) < 128);
;             const float cinit = near ? 0.f : (k0 > qw ? cfar_hi : cfar_lo);
;             if (__builtin_expect(cinit != cbase, 0)) { cbase = cinit; asm volatile("" ::: "memory");
; #pragma unroll
;                 for (int r = 0; r < 16; ++r) cvec[r] = cbase - m_ref; }
.LSPs_skipv:
.LSPs_scal:
	s_cmp_lt_u32 s76, s33
	s_cselect_b64 s[64:65], -1, 0
	s_cmp_gt_i32 s76, s67
	s_cselect_b64 s[80:81], -1, 0
	s_and_b64 s[64:65], s[64:65], s[80:81]
	s_cmp_gt_u32 s76, s28
	s_cselect_b32 s80, s31, s30
	s_cmp_lg_u64 s[64:65], 0
	s_cselect_b32 s98, 0, s80
	s_cmp_eq_u32 s98, s100
	s_cbranch_scc0 .LSPs_cin

; #define ALAS __attribute__((address_space(3)))
; template <bool WIN> ...
;     ...
;             float ls0 = 0.f, ls1 = 0.f;
;     ...
;             union PFU { u32x4 u; bf16x8 b; };
;             PFU p0, p1, p2, p3;
;             AT_EXP(s0, 0, p0);
; #pragma unroll
;             for (int kk = 0; kk < 2; ++kk)
; #pragma unroll
;                 for (int db = 0; db < NDB; ++db) vc[kk * NDB + db] = *(const ALAS bf16x8*)(sb + vx[kk + 2] + db * 4096);
;             __builtin_amdgcn_sched_barrier(0);
; #pragma unroll
;             for (int db = 0; db < NDB; ++db) o[db] = __builtin_amdgcn_mfma_f32_32x32x16_bf16(va[db], p0.b, o[db], 0, 0, 0);
;             AT_EXP(s0, 8, p1);
;             __builtin_amdgcn_sched_barrier(0);
; #pragma unroll
;             for (int db = 0; db < NDB; ++db) o[db] = __builtin_amdgcn_mfma_f32_32x32x16_bf16(va[NDB + db], p1.b, o[db], 0, 0, 0);
;             AT_EXP(s1, 0, p2);
;             __builtin_amdgcn_sched_barrier(0);
; #pragma unroll
;             for (int db = 0; db < NDB; ++db) o[db] = __builtin_amdgcn_mfma_f32_32x32x16_bf16(vc[db], p2.b, o[db], 0, 0, 0);
;             AT_EXP(s1, 8, p3);
;             __builtin_amdgcn_sched_barrier(0);
; #pragma unroll
;             for (int db = 0; db < NDB; ++db) o[db] = __builtin_amdgcn_mfma_f32_32x32x16_bf16(vc[NDB + db], p3.b, o[db], 0, 0, 0);
;             __builtin_amdgcn_sched_barrier(0);
;     ...
;             l_run += ls0 + ls1;
.LSPs_pv:
	s_cmp_eq_u32 s79, 0
	s_cbranch_scc1 .LSPs_pure
	s_waitcnt lgkmcnt(4)
	v_mfma_f32_32x32x16_bf16 v[50:65], v[146:149], v[238:241], v[50:65]
	v_exp_f32_e32 v98, v98
	v_exp_f32_e32 v99, v99
	v_mfma_f32_32x32x16_bf16 v[34:49], v[150:153], v[238:241], v[34:49]
	v_exp_f32_e32 v100, v100
	v_exp_f32_e32 v101, v101
	v_mfma_f32_32x32x16_bf16 v[18:33], v[154:157], v[238:241], v[18:33]
	v_exp_f32_e32 v102, v102
	v_exp_f32_e32 v103, v103
	v_add_f32_e32 v228, v98, v100
	v_add_f32_e32 v229, v99, v101
	v_mfma_f32_32x32x16_bf16 v[2:17], v[158:161], v[238:241], v[2:17]
	v_exp_f32_e32 v104, v104
	v_exp_f32_e32 v105, v105
	v_add_f32_e32 v228, v228, v102
	v_add_f32_e32 v229, v229, v103
	v_add3_u32 v236, s99, v183, v187
	ds_read_b128 v[146:149], v236 offset:16384
	ds_read_b128 v[150:153], v236 offset:20480
	ds_read_b128 v[154:157], v236 offset:24576
	ds_read_b128 v[158:161], v236 offset:28672
	s_waitcnt lgkmcnt(4)
	v_mfma_f32_32x32x16_bf16 v[50:65], v[130:133], v[242:245], v[50:65]
	v_exp_f32_e32 v106, v106
	v_exp_f32_e32 v107, v107
	v_add_f32_e32 v228, v228, v104
	v_add_f32_e32 v229, v229, v105
	v_cvt_pk_bf16_f32 v238, v98, v99
	v_mfma_f32_32x32x16_bf16 v[34:49], v[134:137], v[242:245], v[34:49]
	v_exp_f32_e32 v108, v108
	v_exp_f32_e32 v109, v109
	v_add_f32_e32 v228, v228, v106
	v_add_f32_e32 v229, v229, v107
	v_cvt_pk_bf16_f32 v239, v100, v101
	v_mfma_f32_32x32x16_bf16 v[18:33], v[138:141], v[242:245], v[18:33]
	v_exp_f32_e32 v110, v110
	v_exp_f32_e32 v111, v111
	v_add_f32_e32 v228, v228, v108
	v_add_f32_e32 v229, v229, v109
	v_cvt_pk_bf16_f32 v240, v102, v103
	v_mfma_f32_32x32x16_bf16 v[2:17], v[142:145], v[242:245], v[2:17]
	v_exp_f32_e32 v112, v112
	v_exp_f32_e32 v113, v113
	v_add_f32_e32 v228, v228, v110
	v_add_f32_e32 v229, v229, v111
	v_cvt_pk_bf16_f32 v241, v104, v105
	v_add3_u32 v237, s99, v190, v187
	ds_read_b128 v[130:133], v237 offset:16384
	ds_read_b128 v[134:137], v237 offset:20480
	ds_read_b128 v[138:141], v237 offset:24576
	ds_read_b128 v[142:145], v237 offset:28672
	s_waitcnt lgkmcnt(4)
	v_mfma_f32_32x32x16_bf16 v[50:65], v[146:149], v[246:249], v[50:65]
	v_exp_f32_e32 v82, v82
	v_exp_f32_e32 v83, v83
	v_add_f32_e32 v228, v228, v112
	v_add_f32_e32 v229, v229, v113
	v_cvt_pk_bf16_f32 v242, v106, v107
	v_mfma_f32_32x32x16_bf16 v[34:49], v[150:153], v[246:249], v[34:49]
	v_exp_f32_e32 v84, v84
	v_exp_f32_e32 v85, v85
	v_add_f32_e32 v228, v228, v82
	v_add_f32_e32 v229, v229, v83
	v_cvt_pk_bf16_f32 v243, v108, v109
	v_mfma_f32_32x32x16_bf16 v[18:33], v[154:157], v[246:249], v[18:33]
	v_exp_f32_e32 v86, v86
	v_exp_f32_e32 v87, v87
	v_add_f32_e32 v228, v228, v84
	v_add_f32_e32 v229, v229, v85
	v_cvt_pk_bf16_f32 v244, v110, v111
	v_mfma_f32_32x32x16_bf16 v[2:17], v[158:161], v[246:249], v[2:17]
	v_exp_f32_e32 v88, v88
	v_exp_f32_e32 v89, v89
	v_add_f32_e32 v228, v228, v86
	v_add_f32_e32 v229, v229, v87
	v_cvt_pk_bf16_f32 v245, v112, v113
	s_waitcnt lgkmcnt(0)
	v_mfma_f32_32x32x16_bf16 v[50:65], v[130:133], v[250:253], v[50:65]
	v_exp_f32_e32 v90, v90
	v_exp_f32_e32 v91, v91
	v_add_f32_e32 v228, v228, v88
	v_add_f32_e32 v229, v229, v89
	v_cvt_pk_bf16_f32 v246, v82, v83
	v_mfma_f32_32x32x16_bf16 v[34:49], v[134:137], v[250:253], v[34:49]
	v_exp_f32_e32 v92, v92
	v_exp_f32_e32 v93, v93
	v_add_f32_e32 v228, v228, v90
	v_add_f32_e32 v229, v229, v91
	v_cvt_pk_bf16_f32 v247, v84, v85
	v_mfma_f32_32x32x16_bf16 v[18:33], v[138:141], v[250:253], v[18:33]
	v_exp_f32_e32 v94, v94
	v_exp_f32_e32 v95, v95
	v_add_f32_e32 v228, v228, v92
	v_add_f32_e32 v229, v229, v93
	v_cvt_pk_bf16_f32 v248, v86, v87
	v_mfma_f32_32x32x16_bf16 v[2:17], v[142:145], v[250:253], v[2:17]
	v_exp_f32_e32 v96, v96
	v_exp_f32_e32 v97, v97
	v_add_f32_e32 v228, v228, v94
	v_add_f32_e32 v229, v229, v95
	v_cvt_pk_bf16_f32 v249, v88, v89
	v_add_f32_e32 v228, v228, v96
	v_add_f32_e32 v229, v229, v97
	v_cvt_pk_bf16_f32 v250, v90, v91
	v_cvt_pk_bf16_f32 v251, v92, v93
	v_cvt_pk_bf16_f32 v252, v94, v95
	v_cvt_pk_bf16_f32 v253, v96, v97
	v_add_f32_e32 v228, v228, v229
	v_cmp_nge_f32_e32 vcc, 0x53800000, v228
	s_cbranch_vccnz .LSPs_redo
	s_add_i32 s79, s79, 1
	s_add_i32 s78, s78, 0x8000
	s_addk_i32 s77, 0x100
	s_add_i32 s76, s76, 64
	v_add_f32_e32 v0, v0, v228
	v_lshl_add_u64 v[172:173], v[172:173], 0, s[48:49]
	s_cmpk_eq_i32 s77, 0x2000
	v_lshl_add_u64 v[174:175], v[174:175], 0, s[60:61]
	s_cbranch_scc0 .LSPs_top
	s_branch .LSPs_exit

; template <bool WIN> ...
;     ...
;             const float cinit = near ? 0.f : (k0 > qw ? cfar_hi : cfar_lo);
;             if (__builtin_expect(cinit != cbase, 0)) { cbase = cinit; asm volatile("" ::: "memory");
; #pragma unroll
;                 for (int r = 0; r < 16; ++r) cvec[r] = cbase - m_ref; }
.LSPs_cin:
	v_mov_b32_e32 v98, s98
	s_mov_b32 s100, s98
	v_sub_f32_e32 v82, v98, v201
	v_mov_b32_e32 v202, v98
	v_mov_b32_e32 v66, v82
	v_mov_b32_e32 v67, v82
	v_mov_b32_e32 v68, v82
	v_mov_b32_e32 v69, v82
	v_mov_b32_e32 v70, v82
	v_mov_b32_e32 v71, v82
	v_mov_b32_e32 v72, v82
	v_mov_b32_e32 v73, v82
	v_mov_b32_e32 v74, v82
	v_mov_b32_e32 v75, v82
	v_mov_b32_e32 v76, v82
	v_mov_b32_e32 v77, v82
	v_mov_b32_e32 v78, v82
	v_mov_b32_e32 v79, v82
	v_mov_b32_e32 v80, v82
	v_mov_b32_e32 v81, v82
	s_branch .LSPs_qk
